# P5 epilogue pass 1: x1b bf16 stores merged pairwise into dwordx4 via v_permlane16_swap (13 wide stores instead of 26 narrow)
# baseline (speedup 1.0000x reference)
; __device__ __forceinline__ unsigned cvt_pk_bf16(float lo, float hi) { unsigned r; asm volatile("v_cvt_pk_bf16_f32 %0, %1, %2" : "=v"(r) : "v"(lo), "v"(hi)); return r; }
;     __device__ __forceinline__ void fused(f32x4 (&acc)[2][2][4][2], const Unit& u, int wr, int wc, int fr, int fq, LAS unsigned char* lds, int wid, int lane) const {
;     ...
;           for (int ai = 0; ai < 2; ++ai)
; #pragma unroll
;             for (int m = 0; m < 4; ++m) { const size_t off = (size_t)(row0 + ai * HALF + m * 16) * DM + col0;
; #pragma unroll
;                 for (int bj = 0; bj < 2; ++bj)
; #pragma unroll
;                     for (int n = 0; n < 2; ++n) { const f32x4 xv = *(const f32x4*)(base + off + bj * HALF + n * 16); const f32x4 o = xv + gv[bj][n] * acc[ai][bj][m][n];
;                         u32x2 w; w.x = cvt_pk_bf16(o[0], o[1]); w.y = cvt_pk_bf16(o[2], o[3]); *(u32x2*)(x1b + off + bj * HALF + n * 16) = w; acc[ai][bj][m][n] = o; }
;                 asm volatile("" ::: "memory"); } }
.LBB0_582:
	v_bfe_u32 v180, v170, 4, 1
	v_mul_u32_u24_e32 v180, 24, v180
	v_mov_b32_e32 v181, 0
	s_add_u32 s0, s34, 0xd200000
	s_addc_u32 s1, s35, 0
	s_lshl_b32 s11, s7, 5
	s_lshl_b32 s12, s8, 8
	s_or_b32 s11, s12, s11
	s_lshl_b32 s10, s6, 8
	v_and_or_b32 v144, v140, 12, s11
	s_ashr_i32 s11, s6, 3
	s_add_i32 s14, s10, s54
	s_mul_hi_i32 s13, s11, 0x6000
	s_mulk_i32 s11, 0x6000
	s_add_u32 s12, s34, s11
	v_or_b32_e32 v150, s14, v153
	s_addc_u32 s13, s35, s13
	v_ashrrev_i32_e32 v145, 31, v144
	v_ashrrev_i32_e32 v151, 31, v150
	v_lshl_add_u64 v[146:147], v[144:145], 2, s[12:13]
	s_movk_i32 s11, 0x2000
	v_lshlrev_b64 v[130:131], 10, v[150:151]
	v_add_co_u32_e32 v128, vcc, s11, v146
	v_lshl_add_u64 v[148:149], v[130:131], 0, v[144:145]
	s_nop 0
	v_addc_co_u32_e32 v129, vcc, 0, v147, vcc
	v_lshl_add_u64 v[158:159], v[148:149], 2, s[36:37]
	s_barrier
	global_load_dwordx4 v[154:157], v[158:159], off
	global_load_dwordx4 v[140:143], v[128:129], off
	global_load_dwordx4 v[136:139], v[128:129], off offset:64
	global_load_dwordx4 v[132:135], v[128:129], off offset:512
	s_nop 0
	global_load_dwordx4 v[128:131], v[128:129], off offset:576
	v_lshl_add_u64 v[160:161], v[148:149], 1, s[0:1]
	s_mov_b64 s[12:13], 0x20000
	s_waitcnt vmcnt(0)
	v_pk_fma_f32 v[126:127], v[126:127], v[142:143], v[156:157]
	v_pk_fma_f32 v[124:125], v[124:125], v[140:141], v[154:155]
	s_nop 0
	v_cvt_pk_bf16_f32 v176, v124, v125
	v_cvt_pk_bf16_f32 v177, v126, v127
	global_load_dwordx4 v[154:157], v[158:159], off offset:64
	s_waitcnt vmcnt(0)
	v_pk_fma_f32 v[122:123], v[122:123], v[138:139], v[156:157]
	v_pk_fma_f32 v[120:121], v[120:121], v[136:137], v[154:155]
	s_nop 0
	v_cvt_pk_bf16_f32 v178, v120, v121
	v_cvt_pk_bf16_f32 v179, v122, v123
	s_nop 1
	v_permlane16_swap_b32_e32 v176, v178
	v_permlane16_swap_b32_e32 v177, v179
	v_lshl_add_u64 v[182:183], v[160:161], 0, v[180:181]
	global_store_dwordx4 v[182:183], v[176:179], off
	global_load_dwordx4 v[154:157], v[158:159], off offset:512
	s_waitcnt vmcnt(0)
	v_pk_fma_f32 v[118:119], v[118:119], v[134:135], v[156:157]
	v_pk_fma_f32 v[116:117], v[116:117], v[132:133], v[154:155]
	s_nop 0
	v_cvt_pk_bf16_f32 v176, v116, v117
	v_cvt_pk_bf16_f32 v177, v118, v119
	global_load_dwordx4 v[154:157], v[158:159], off offset:576
	v_or_b32_e32 v158, 16, v150
	v_ashrrev_i32_e32 v159, 31, v158
	v_lshlrev_b64 v[158:159], 10, v[158:159]
	v_lshl_add_u64 v[158:159], v[158:159], 0, v[144:145]
	v_lshl_add_u64 v[162:163], v[158:159], 2, s[36:37]
	v_lshl_add_u64 v[158:159], v[158:159], 1, s[0:1]
	s_waitcnt vmcnt(0)
	v_pk_fma_f32 v[110:111], v[110:111], v[130:131], v[156:157]
	v_pk_fma_f32 v[108:109], v[108:109], v[128:129], v[154:155]
	s_nop 0
	v_cvt_pk_bf16_f32 v178, v108, v109
	v_cvt_pk_bf16_f32 v179, v110, v111
	s_nop 1
	v_permlane16_swap_b32_e32 v176, v178
	v_permlane16_swap_b32_e32 v177, v179
	v_lshl_add_u64 v[182:183], v[160:161], 0, v[180:181]
	global_store_dwordx4 v[182:183], v[176:179], off offset:256
	global_load_dwordx4 v[154:157], v[162:163], off
	v_or_b32_e32 v160, 32, v150
	v_ashrrev_i32_e32 v161, 31, v160
	v_lshlrev_b64 v[160:161], 10, v[160:161]
	v_lshl_add_u64 v[160:161], v[160:161], 0, v[144:145]
	v_or_b32_e32 v150, 48, v150
	v_ashrrev_i32_e32 v151, 31, v150
	v_lshlrev_b64 v[150:151], 10, v[150:151]
	v_lshl_add_u64 v[150:151], v[150:151], 0, v[144:145]
	s_waitcnt vmcnt(0)
	v_pk_fma_f32 v[114:115], v[114:115], v[142:143], v[156:157]
	v_pk_fma_f32 v[112:113], v[112:113], v[140:141], v[154:155]
	s_nop 0
	v_cvt_pk_bf16_f32 v176, v112, v113
	v_cvt_pk_bf16_f32 v177, v114, v115
	global_load_dwordx4 v[154:157], v[162:163], off offset:64
	s_waitcnt vmcnt(0)
	v_pk_fma_f32 v[106:107], v[106:107], v[138:139], v[156:157]
	v_pk_fma_f32 v[104:105], v[104:105], v[136:137], v[154:155]
	s_nop 0
	v_cvt_pk_bf16_f32 v178, v104, v105
	v_cvt_pk_bf16_f32 v179, v106, v107
	s_nop 1
	v_permlane16_swap_b32_e32 v176, v178
	v_permlane16_swap_b32_e32 v177, v179
	v_lshl_add_u64 v[182:183], v[158:159], 0, v[180:181]
	global_store_dwordx4 v[182:183], v[176:179], off
	global_load_dwordx4 v[154:157], v[162:163], off offset:512
	s_waitcnt vmcnt(0)
	v_pk_fma_f32 v[102:103], v[102:103], v[134:135], v[156:157]
	v_pk_fma_f32 v[100:101], v[100:101], v[132:133], v[154:155]
	s_nop 0
	v_cvt_pk_bf16_f32 v176, v100, v101
	v_cvt_pk_bf16_f32 v177, v102, v103
	global_load_dwordx4 v[154:157], v[162:163], off offset:576
	v_lshl_add_u64 v[162:163], v[160:161], 2, s[36:37]
	s_waitcnt vmcnt(0)
	v_pk_fma_f32 v[94:95], v[94:95], v[130:131], v[156:157]
	v_pk_fma_f32 v[92:93], v[92:93], v[128:129], v[154:155]
	s_nop 0
	v_cvt_pk_bf16_f32 v178, v92, v93
	v_cvt_pk_bf16_f32 v179, v94, v95
	s_nop 1
	v_permlane16_swap_b32_e32 v176, v178
	v_permlane16_swap_b32_e32 v177, v179
	v_lshl_add_u64 v[182:183], v[158:159], 0, v[180:181]
	global_store_dwordx4 v[182:183], v[176:179], off offset:256
	global_load_dwordx4 v[154:157], v[162:163], off
	v_lshl_add_u64 v[158:159], v[160:161], 1, s[0:1]
	v_lshl_add_u64 v[160:161], v[150:151], 2, s[36:37]
	v_lshl_add_u64 v[150:151], v[150:151], 1, s[0:1]
	s_waitcnt vmcnt(0)
	v_pk_fma_f32 v[98:99], v[98:99], v[142:143], v[156:157]
	v_pk_fma_f32 v[96:97], v[96:97], v[140:141], v[154:155]
	s_nop 0
	v_cvt_pk_bf16_f32 v176, v96, v97
	v_cvt_pk_bf16_f32 v177, v98, v99
	global_load_dwordx4 v[154:157], v[162:163], off offset:64
	s_waitcnt vmcnt(0)
	v_pk_fma_f32 v[90:91], v[90:91], v[138:139], v[156:157]
	v_pk_fma_f32 v[88:89], v[88:89], v[136:137], v[154:155]
	s_nop 0
	v_cvt_pk_bf16_f32 v178, v88, v89
	v_cvt_pk_bf16_f32 v179, v90, v91
	s_nop 1
	v_permlane16_swap_b32_e32 v176, v178
	v_permlane16_swap_b32_e32 v177, v179
	v_lshl_add_u64 v[182:183], v[158:159], 0, v[180:181]
	global_store_dwordx4 v[182:183], v[176:179], off
	global_load_dwordx4 v[154:157], v[162:163], off offset:512
	s_waitcnt vmcnt(0)
; __device__ __forceinline__ unsigned cvt_pk_bf16(float lo, float hi) { unsigned r; asm volatile("v_cvt_pk_bf16_f32 %0, %1, %2" : "=v"(r) : "v"(lo), "v"(hi)); return r; }
;     __device__ __forceinline__ void fused(f32x4 (&acc)[2][2][4][2], const Unit& u, int wr, int wc, int fr, int fq, LAS unsigned char* lds, int wid, int lane) const {
;     ...
;           for (int ai = 0; ai < 2; ++ai)
; #pragma unroll
;             for (int m = 0; m < 4; ++m) { const size_t off = (size_t)(row0 + ai * HALF + m * 16) * DM + col0;
; #pragma unroll
;                 for (int bj = 0; bj < 2; ++bj)
; #pragma unroll
;                     for (int n = 0; n < 2; ++n) { const f32x4 xv = *(const f32x4*)(base + off + bj * HALF + n * 16); const f32x4 o = xv + gv[bj][n] * acc[ai][bj][m][n];
;                         u32x2 w; w.x = cvt_pk_bf16(o[0], o[1]); w.y = cvt_pk_bf16(o[2], o[3]); *(u32x2*)(x1b + off + bj * HALF + n * 16) = w; acc[ai][bj][m][n] = o; }
;                 asm volatile("" ::: "memory"); } }
	v_pk_fma_f32 v[86:87], v[86:87], v[134:135], v[156:157]
	v_pk_fma_f32 v[84:85], v[84:85], v[132:133], v[154:155]
	s_nop 0
	v_cvt_pk_bf16_f32 v176, v84, v85
	v_cvt_pk_bf16_f32 v177, v86, v87
	global_load_dwordx4 v[154:157], v[162:163], off offset:576
	s_waitcnt vmcnt(0)
	v_pk_fma_f32 v[78:79], v[78:79], v[130:131], v[156:157]
	v_pk_fma_f32 v[76:77], v[76:77], v[128:129], v[154:155]
	s_nop 0
	v_cvt_pk_bf16_f32 v178, v76, v77
	v_cvt_pk_bf16_f32 v179, v78, v79
	s_nop 1
	v_permlane16_swap_b32_e32 v176, v178
	v_permlane16_swap_b32_e32 v177, v179
	v_lshl_add_u64 v[182:183], v[158:159], 0, v[180:181]
	global_store_dwordx4 v[182:183], v[176:179], off offset:256
	global_load_dwordx4 v[154:157], v[160:161], off
	v_lshl_add_u64 v[158:159], v[148:149], 0, s[12:13]
	s_mov_b64 s[12:13], 0x24000
	s_waitcnt vmcnt(0)
	v_pk_fma_f32 v[82:83], v[82:83], v[142:143], v[156:157]
	v_pk_fma_f32 v[80:81], v[80:81], v[140:141], v[154:155]
	s_nop 0
	v_cvt_pk_bf16_f32 v176, v80, v81
	v_cvt_pk_bf16_f32 v177, v82, v83
	global_load_dwordx4 v[154:157], v[160:161], off offset:64
	s_waitcnt vmcnt(0)
	v_pk_fma_f32 v[74:75], v[74:75], v[138:139], v[156:157]
	v_pk_fma_f32 v[72:73], v[72:73], v[136:137], v[154:155]
	s_nop 0
	v_cvt_pk_bf16_f32 v178, v72, v73
	v_cvt_pk_bf16_f32 v179, v74, v75
	s_nop 1
	v_permlane16_swap_b32_e32 v176, v178
	v_permlane16_swap_b32_e32 v177, v179
	v_lshl_add_u64 v[182:183], v[150:151], 0, v[180:181]
	global_store_dwordx4 v[182:183], v[176:179], off
	global_load_dwordx4 v[154:157], v[160:161], off offset:512
	s_waitcnt vmcnt(0)
	v_pk_fma_f32 v[70:71], v[70:71], v[134:135], v[156:157]
	v_pk_fma_f32 v[68:69], v[68:69], v[132:133], v[154:155]
	s_nop 0
	v_cvt_pk_bf16_f32 v176, v68, v69
	v_cvt_pk_bf16_f32 v177, v70, v71
	global_load_dwordx4 v[154:157], v[160:161], off offset:576
	v_lshl_add_u64 v[160:161], v[158:159], 2, s[36:37]
	s_waitcnt vmcnt(0)
	v_pk_fma_f32 v[66:67], v[66:67], v[130:131], v[156:157]
	v_pk_fma_f32 v[64:65], v[64:65], v[128:129], v[154:155]
	s_nop 0
	v_cvt_pk_bf16_f32 v178, v64, v65
	v_cvt_pk_bf16_f32 v179, v66, v67
	s_nop 1
	v_permlane16_swap_b32_e32 v176, v178
	v_permlane16_swap_b32_e32 v177, v179
	v_lshl_add_u64 v[182:183], v[150:151], 0, v[180:181]
	global_store_dwordx4 v[182:183], v[176:179], off offset:256
	global_load_dwordx4 v[154:157], v[160:161], off
	v_lshl_add_u64 v[150:151], v[158:159], 1, s[0:1]
	v_lshl_add_u64 v[158:159], v[148:149], 0, s[12:13]
	s_mov_b64 s[12:13], 0x28000
	s_waitcnt vmcnt(0)
	v_pk_fma_f32 v[62:63], v[62:63], v[142:143], v[156:157]
	v_pk_fma_f32 v[60:61], v[60:61], v[140:141], v[154:155]
	s_nop 0
	v_cvt_pk_bf16_f32 v176, v60, v61
	v_cvt_pk_bf16_f32 v177, v62, v63
	global_load_dwordx4 v[154:157], v[160:161], off offset:64
	s_waitcnt vmcnt(0)
	v_pk_fma_f32 v[58:59], v[58:59], v[138:139], v[156:157]
	v_pk_fma_f32 v[56:57], v[56:57], v[136:137], v[154:155]
	s_nop 0
	v_cvt_pk_bf16_f32 v178, v56, v57
	v_cvt_pk_bf16_f32 v179, v58, v59
	s_nop 1
	v_permlane16_swap_b32_e32 v176, v178
	v_permlane16_swap_b32_e32 v177, v179
	v_lshl_add_u64 v[182:183], v[150:151], 0, v[180:181]
	global_store_dwordx4 v[182:183], v[176:179], off
	global_load_dwordx4 v[154:157], v[160:161], off offset:512
	s_waitcnt vmcnt(0)
	v_pk_fma_f32 v[54:55], v[54:55], v[134:135], v[156:157]
	v_pk_fma_f32 v[52:53], v[52:53], v[132:133], v[154:155]
	s_nop 0
	v_cvt_pk_bf16_f32 v176, v52, v53
	v_cvt_pk_bf16_f32 v177, v54, v55
	global_load_dwordx4 v[154:157], v[160:161], off offset:576
	v_lshl_add_u64 v[160:161], v[158:159], 2, s[36:37]
	s_waitcnt vmcnt(0)
	v_pk_fma_f32 v[46:47], v[46:47], v[130:131], v[156:157]
	v_pk_fma_f32 v[44:45], v[44:45], v[128:129], v[154:155]
	s_nop 0
	v_cvt_pk_bf16_f32 v178, v44, v45
	v_cvt_pk_bf16_f32 v179, v46, v47
	s_nop 1
	v_permlane16_swap_b32_e32 v176, v178
	v_permlane16_swap_b32_e32 v177, v179
	v_lshl_add_u64 v[182:183], v[150:151], 0, v[180:181]
	global_store_dwordx4 v[182:183], v[176:179], off offset:256
	global_load_dwordx4 v[154:157], v[160:161], off
	v_lshl_add_u64 v[150:151], v[158:159], 1, s[0:1]
	v_lshl_add_u64 v[158:159], v[148:149], 0, s[12:13]
	s_mov_b64 s[12:13], 0x2c000
	s_waitcnt vmcnt(0)
	v_pk_fma_f32 v[50:51], v[50:51], v[142:143], v[156:157]
	v_pk_fma_f32 v[48:49], v[48:49], v[140:141], v[154:155]
	s_nop 0
	v_cvt_pk_bf16_f32 v176, v48, v49
	v_cvt_pk_bf16_f32 v177, v50, v51
	global_load_dwordx4 v[154:157], v[160:161], off offset:64
	s_waitcnt vmcnt(0)
	v_pk_fma_f32 v[42:43], v[42:43], v[138:139], v[156:157]
	v_pk_fma_f32 v[40:41], v[40:41], v[136:137], v[154:155]
	s_nop 0
	v_cvt_pk_bf16_f32 v178, v40, v41
	v_cvt_pk_bf16_f32 v179, v42, v43
	s_nop 1
	v_permlane16_swap_b32_e32 v176, v178
	v_permlane16_swap_b32_e32 v177, v179
	v_lshl_add_u64 v[182:183], v[150:151], 0, v[180:181]
	global_store_dwordx4 v[182:183], v[176:179], off
	global_load_dwordx4 v[154:157], v[160:161], off offset:512
	s_waitcnt vmcnt(0)
; __device__ __forceinline__ unsigned cvt_pk_bf16(float lo, float hi) { unsigned r; asm volatile("v_cvt_pk_bf16_f32 %0, %1, %2" : "=v"(r) : "v"(lo), "v"(hi)); return r; }
;     __device__ __forceinline__ void run(const f32x4 (&v)[2][2][4][2], const Unit& u, int wr, int wc, int fr, int fq, LAS unsigned char* lds, int wid, int lane) const {
;     ...
;         for (int ai = 0; ai < 2; ++ai)
; #pragma unroll
;             for (int m = 0; m < 4; ++m) { float s = 0.f;
; #pragma unroll
;                 for (int bj = 0; bj < 2; ++bj)
; #pragma unroll
;                     for (int n = 0; n < 2; ++n) { const f32x4 x = v[ai][bj][m][n]; s += (x[0] * x[0] + x[1] * x[1]) + (x[2] * x[2] + x[3] * x[3]); }
;                 s += __shfl_xor(s, 16); s += __shfl_xor(s, 32);
;                 if (fq == 0) P[(ai * HALF + wr * 64 + m * 16 + fr) * 4 + wc] = s; }
;     __device__ __forceinline__ void fused(f32x4 (&acc)[2][2][4][2], const Unit& u, int wr, int wc, int fr, int fq, LAS unsigned char* lds, int wid, int lane) const {
;     ...
;                 for (int bj = 0; bj < 2; ++bj)
; #pragma unroll
;                     for (int n = 0; n < 2; ++n) { const f32x4 xv = *(const f32x4*)(base + off + bj * HALF + n * 16); const f32x4 o = xv + gv[bj][n] * acc[ai][bj][m][n];
;                         u32x2 w; w.x = cvt_pk_bf16(o[0], o[1]); w.y = cvt_pk_bf16(o[2], o[3]); *(u32x2*)(x1b + off + bj * HALF + n * 16) = w; acc[ai][bj][m][n] = o; }
;                 asm volatile("" ::: "memory"); } }
	v_pk_fma_f32 v[38:39], v[38:39], v[134:135], v[156:157]
	v_pk_fma_f32 v[36:37], v[36:37], v[132:133], v[154:155]
	s_nop 0
	v_cvt_pk_bf16_f32 v176, v36, v37
	v_cvt_pk_bf16_f32 v177, v38, v39
	global_load_dwordx4 v[154:157], v[160:161], off offset:576
	v_lshl_add_u64 v[160:161], v[158:159], 2, s[36:37]
	s_waitcnt vmcnt(0)
	v_pk_fma_f32 v[30:31], v[30:31], v[130:131], v[156:157]
	v_pk_fma_f32 v[28:29], v[28:29], v[128:129], v[154:155]
	s_nop 0
	v_cvt_pk_bf16_f32 v178, v28, v29
	v_cvt_pk_bf16_f32 v179, v30, v31
	s_nop 1
	v_permlane16_swap_b32_e32 v176, v178
	v_permlane16_swap_b32_e32 v177, v179
	v_lshl_add_u64 v[182:183], v[150:151], 0, v[180:181]
	global_store_dwordx4 v[182:183], v[176:179], off offset:256
	global_load_dwordx4 v[154:157], v[160:161], off
	v_lshl_add_u64 v[150:151], v[158:159], 1, s[0:1]
	v_lshl_add_u64 v[158:159], v[148:149], 0, s[12:13]
	s_waitcnt vmcnt(0)
	v_pk_fma_f32 v[34:35], v[34:35], v[142:143], v[156:157]
	v_pk_fma_f32 v[32:33], v[32:33], v[140:141], v[154:155]
	s_nop 0
	v_cvt_pk_bf16_f32 v176, v32, v33
	v_cvt_pk_bf16_f32 v177, v34, v35
	global_load_dwordx4 v[154:157], v[160:161], off offset:64
	s_waitcnt vmcnt(0)
	v_pk_fma_f32 v[26:27], v[26:27], v[138:139], v[156:157]
	v_pk_fma_f32 v[24:25], v[24:25], v[136:137], v[154:155]
	s_nop 0
	v_cvt_pk_bf16_f32 v178, v24, v25
	v_cvt_pk_bf16_f32 v179, v26, v27
	s_nop 1
	v_permlane16_swap_b32_e32 v176, v178
	v_permlane16_swap_b32_e32 v177, v179
	v_lshl_add_u64 v[182:183], v[150:151], 0, v[180:181]
	global_store_dwordx4 v[182:183], v[176:179], off
	global_load_dwordx4 v[154:157], v[160:161], off offset:512
	s_waitcnt vmcnt(0)
	v_pk_fma_f32 v[22:23], v[22:23], v[134:135], v[156:157]
	v_pk_fma_f32 v[20:21], v[20:21], v[132:133], v[154:155]
	s_nop 0
	v_cvt_pk_bf16_f32 v154, v20, v21
	v_cvt_pk_bf16_f32 v155, v22, v23
	global_store_dwordx2 v[150:151], v[154:155], off offset:256
	global_load_dwordx4 v[154:157], v[160:161], off offset:576
	v_lshl_add_u64 v[160:161], v[158:159], 2, s[36:37]
	s_waitcnt vmcnt(0)
	v_pk_fma_f32 v[14:15], v[14:15], v[130:131], v[156:157]
	v_pk_fma_f32 v[12:13], v[12:13], v[128:129], v[154:155]
	v_lshl_add_u64 v[154:155], v[158:159], 1, s[0:1]
	v_cvt_pk_bf16_f32 v148, v12, v13
	v_cvt_pk_bf16_f32 v149, v14, v15
	global_store_dwordx2 v[150:151], v[148:149], off offset:288
	global_load_dwordx4 v[148:151], v[160:161], off
	s_lshl_b32 s0, s7, 2
	s_add_i32 s7, s0, 0
	s_waitcnt vmcnt(0)
	v_pk_fma_f32 v[142:143], v[18:19], v[142:143], v[150:151]
	v_pk_fma_f32 v[140:141], v[16:17], v[140:141], v[148:149]
	s_nop 0
	v_cvt_pk_bf16_f32 v16, v140, v141
	v_cvt_pk_bf16_f32 v17, v142, v143
	global_store_dwordx2 v[154:155], v[16:17], off
	global_load_dwordx4 v[148:151], v[160:161], off offset:64
	s_waitcnt vmcnt(0)
	v_pk_fma_f32 v[16:17], v[10:11], v[138:139], v[150:151]
	v_pk_fma_f32 v[18:19], v[8:9], v[136:137], v[148:149]
	s_nop 0
	v_cvt_pk_bf16_f32 v8, v18, v19
	v_cvt_pk_bf16_f32 v9, v16, v17
	global_store_dwordx2 v[154:155], v[8:9], off offset:32
	global_load_dwordx4 v[136:139], v[160:161], off offset:512
	s_waitcnt vmcnt(0)
	v_pk_fma_f32 v[8:9], v[6:7], v[134:135], v[138:139]
	v_pk_fma_f32 v[10:11], v[4:5], v[132:133], v[136:137]
	v_mul_f32_e32 v7, v127, v127
	v_cvt_pk_bf16_f32 v4, v10, v11
	v_cvt_pk_bf16_f32 v5, v8, v9
	global_store_dwordx2 v[154:155], v[4:5], off offset:256
	global_load_dwordx4 v[136:139], v[160:161], off offset:576
	v_mbcnt_lo_u32_b32 v4, -1, 0
	v_mbcnt_hi_u32_b32 v4, -1, v4
	v_and_b32_e32 v6, 64, v4
	v_xor_b32_e32 v5, 16, v4
	v_add_u32_e32 v6, 64, v6
	v_cmp_lt_i32_e32 vcc, v5, v6
	v_fmac_f32_e32 v7, v126, v126
	v_mul_f32_e32 v134, v123, v123
	v_cndmask_b32_e32 v5, v4, v5, vcc
	v_lshlrev_b32_e32 v133, 2, v5
	v_mul_f32_e32 v5, v125, v125
	v_fmac_f32_e32 v5, v124, v124
	v_add_f32_e32 v5, v5, v7
	v_mul_f32_e32 v7, v121, v121
	v_fmac_f32_e32 v7, v120, v120
	v_fmac_f32_e32 v134, v122, v122
	v_add_f32_e32 v7, v7, v134
	v_add_f32_e32 v5, v5, v7
	v_mul_f32_e32 v7, v117, v117
	v_mul_f32_e32 v134, v119, v119
	v_fmac_f32_e32 v7, v116, v116
	v_fmac_f32_e32 v134, v118, v118
	v_add_f32_e32 v7, v7, v134
	v_add_f32_e32 v5, v5, v7
	v_mul_f32_e32 v7, v109, v109
	v_mul_f32_e32 v134, v111, v111
	v_fmac_f32_e32 v7, v108, v108
	v_fmac_f32_e32 v134, v110, v110
	v_add_f32_e32 v7, v7, v134
	v_add_f32_e32 v5, v5, v7
	ds_bpermute_b32 v7, v133, v5
	v_xor_b32_e32 v134, 32, v4
	v_cmp_lt_i32_e32 vcc, v134, v6
	v_and_b32_e32 v132, 63, v170
	s_waitcnt lgkmcnt(0)
	v_add_f32_e32 v135, v5, v7
	v_cndmask_b32_e32 v4, v4, v134, vcc
	v_lshlrev_b32_e32 v134, 2, v4
	v_cmp_gt_u32_e32 vcc, 16, v132
	s_waitcnt vmcnt(0)
	v_pk_fma_f32 v[6:7], v[0:1], v[128:129], v[136:137]
	s_nop 0
	v_cvt_pk_bf16_f32 v0, v6, v7
	v_pk_fma_f32 v[4:5], v[2:3], v[130:131], v[138:139]
	s_nop 0
	v_cvt_pk_bf16_f32 v1, v4, v5
	global_store_dwordx2 v[154:155], v[0:1], off offset:288
	ds_bpermute_b32 v0, v134, v135
	s_and_saveexec_b64 s[0:1], vcc
	v_readlane_b32 s56, v240, 6
	v_readlane_b32 s58, v240, 8
	v_readlane_b32 s57, v240, 7
	v_readlane_b32 s59, v240, 9
	s_cbranch_execz .LBB0_584
	s_lshl_b32 s11, s51, 10
	s_add_i32 s11, s7, s11
	v_lshl_add_u32 v1, v153, 4, s11
	s_waitcnt lgkmcnt(0)
	v_add_f32_e32 v0, v135, v0
	ds_write_b32 v1, v0
